# conv-out/GLU epilogues too: loads hoisted with counted waits, LDS-DMA stage after them (on top of v40)
# speedup vs baseline: 1.0156x; 1.0035x over previous
.LBB0_549:
	s_add_i32 s4, s56, s64
	v_cndmask_b32_e64 v130, v205, 0, s[22:23]
	s_add_i32 s33, s4, 0x80
	v_sub_u32_e32 v253, v1, v130
	s_mov_b32 s98, s33
	v_cndmask_b32_e64 v130, v206, 0, s[22:23]
	v_sub_u32_e32 v254, v202, v130
	s_mov_b64 s[22:23], -1
	s_lshl_b32 s4, s58, 8
	s_add_i32 s4, s4, s34
	s_and_b64 vcc, exec, s[20:21]
	s_cbranch_vccz .LBB0_552
	v_mov_b32_e32 v130, v207
	v_mov_b32_e32 v131, v208
	s_lshl_b32 s20, s57, 7
	v_add_u32_e32 v136, s4, v130
	s_or_b32 s20, s20, s35
	v_and_b32_e32 v130, 1, v131
	v_ashrrev_i32_e32 v137, 31, v136
	v_lshl_add_u32 v134, v131, 3, s20
	v_cmp_eq_u32_e32 vcc, 1, v130
	v_lshlrev_b64 v[130:131], 10, v[136:137]
	v_ashrrev_i32_e32 v135, 31, v134
	v_lshl_add_u64 v[130:131], s[74:75], 0, v[130:131]
	v_cndmask_b32_e32 v194, 0, v221, vcc
	v_lshl_add_u64 v[130:131], v[130:131], 0, v[134:135]
	v_lshl_add_u64 v[130:131], v[130:131], 0, v[194:195]
	v_lshlrev_b32_e32 v250, 10, v136
	v_add3_u32 v250, v250, v134, v194
	v_lshlrev_b32_e32 v251, 11, v136
	v_lshl_add_u32 v251, v134, 1, v251
	global_load_dwordx4 v[170:173], v250, s[74:75]
	global_load_dwordx4 v[174:177], v251, s[10:11]
	v_add_u32_e32 v251, 0x8000, v251
	global_load_dwordx4 v[178:181], v251, s[10:11]
	v_add_u32_e32 v250, 0x8000, v250
	global_load_dwordx4 v[182:185], v250, s[74:75]
	v_add_u32_e32 v251, 0x8000, v251
	global_load_dwordx4 v[186:189], v251, s[10:11]
	v_add_u32_e32 v251, 0x8000, v251
	global_load_dwordx4 v[190:193], v251, s[10:11]
	v_add_u32_e32 v250, 0x18000, v250
	global_load_dwordx4 v[238:241], v250, s[74:75]
	v_add_u32_e32 v251, 0x28000, v251
	global_load_dwordx4 v[242:245], v251, s[10:11]
	v_add_u32_e32 v251, 0x8000, v251
	global_load_dwordx4 v[246:249], v251, s[10:11]
	s_mov_b32 s99, s4
	s_mov_b32 s4, s70
	s_mov_b32 m0, s43
	s_nop 0
	buffer_load_dwordx4 v253, s[4:7], s98 offen lds
	s_mov_b32 m0, s44
	s_nop 0
	buffer_load_dwordx4 v254, s[4:7], s98 offen lds
	s_mov_b32 s4, s99
	v_lshlrev_b64 v[130:131], 11, v[136:137]
	v_lshlrev_b64 v[132:133], 1, v[134:135]
	v_lshl_add_u64 v[130:131], s[10:11], 0, v[130:131]
	v_lshl_add_u64 v[130:131], v[130:131], 0, v[132:133]
	v_exp_f32_e32 v146, v94
	v_exp_f32_e32 v147, v95
	v_exp_f32_e32 v148, v96
	v_exp_f32_e32 v149, v97
	v_exp_f32_e32 v150, v90
	v_exp_f32_e32 v152, v92
	v_exp_f32_e32 v153, v93
	v_exp_f32_e32 v151, v91
	v_pk_add_f32 v[148:149], v[148:149], 1.0 op_sel_hi:[1,0]
	v_pk_add_f32 v[146:147], v[146:147], 1.0 op_sel_hi:[1,0]
	v_pk_add_f32 v[152:153], v[152:153], 1.0 op_sel_hi:[1,0]
	v_pk_add_f32 v[150:151], v[150:151], 1.0 op_sel_hi:[1,0]
	v_rcp_f32_e32 v146, v146
	v_rcp_f32_e32 v147, v147
	v_rcp_f32_e32 v148, v148
	v_rcp_f32_e32 v149, v149
	v_rcp_f32_e32 v150, v150
	v_rcp_f32_e32 v151, v151
	v_rcp_f32_e32 v152, v152
	v_rcp_f32_e32 v153, v153
	v_add_co_u32_e32 v154, vcc, s42, v130
	s_mov_b32 s20, 0x18000
	s_nop 0
	v_addc_co_u32_e32 v155, vcc, 0, v131, vcc
	s_waitcnt vmcnt(10)
	v_mov_b32_e32 v137, v172
	v_mov_b32_e32 v166, v173
	s_nop 0
	v_mov_b32_e32 v138, v170
	s_nop 1
	v_permlane16_swap_b32_e32 v138, v137
	v_mov_b32_e32 v139, v171
	s_nop 1
	v_permlane16_swap_b32_e32 v139, v166
	v_cvt_f32_ubyte3_e32 v159, v138
	v_cvt_f32_ubyte2_e32 v158, v138
	v_cvt_f32_ubyte1_e32 v161, v138
	v_cvt_f32_ubyte0_e32 v160, v138
	v_cvt_f32_ubyte3_e32 v163, v139
	v_cvt_f32_ubyte2_e32 v162, v139
	v_cvt_f32_ubyte1_e32 v165, v139
	v_cvt_f32_ubyte0_e32 v164, v139
	s_waitcnt vmcnt(9)
	v_lshlrev_b32_e32 v140, 16, v174
	v_and_b32_e32 v141, 0xffff0000, v174
	v_lshlrev_b32_e32 v142, 16, v175
	v_and_b32_e32 v143, 0xffff0000, v175
	v_lshlrev_b32_e32 v156, 16, v176
	v_and_b32_e32 v157, 0xffff0000, v176
	v_lshlrev_b32_e32 v144, 16, v177
	v_and_b32_e32 v145, 0xffff0000, v177
	v_pk_mul_f32 v[138:139], v[126:127], v[160:161]
	v_pk_mul_f32 v[158:159], v[128:129], v[158:159]
	v_pk_mul_f32 v[160:161], v[122:123], v[164:165]
	v_pk_mul_f32 v[162:163], v[124:125], v[162:163]
	v_pk_fma_f32 v[142:143], v[148:149], v[158:159], v[142:143]
	v_pk_fma_f32 v[138:139], v[146:147], v[138:139], v[140:141]
	v_pk_fma_f32 v[144:145], v[152:153], v[162:163], v[144:145]
	v_pk_fma_f32 v[140:141], v[150:151], v[160:161], v[156:157]
	v_cvt_pk_bf16_f32 v138, v138, v139
	v_cvt_pk_bf16_f32 v139, v142, v143
	v_exp_f32_e32 v146, v86
	v_cvt_pk_bf16_f32 v140, v140, v141
	v_cvt_pk_bf16_f32 v141, v144, v145
	v_exp_f32_e32 v147, v87
	v_exp_f32_e32 v148, v88
	v_exp_f32_e32 v149, v89
	v_exp_f32_e32 v150, v82
	v_exp_f32_e32 v151, v83
	v_exp_f32_e32 v152, v84
	v_exp_f32_e32 v153, v85
	v_pk_add_f32 v[148:149], v[148:149], 1.0 op_sel_hi:[1,0]
	v_pk_add_f32 v[146:147], v[146:147], 1.0 op_sel_hi:[1,0]
	v_add_u32_e32 v156, 32, v136
	v_pk_add_f32 v[152:153], v[152:153], 1.0 op_sel_hi:[1,0]
	v_pk_add_f32 v[150:151], v[150:151], 1.0 op_sel_hi:[1,0]
	v_rcp_f32_e32 v146, v146
	v_rcp_f32_e32 v147, v147
	v_rcp_f32_e32 v148, v148
	v_rcp_f32_e32 v149, v149
	v_ashrrev_i32_e32 v157, 31, v156
	v_rcp_f32_e32 v150, v150
	v_rcp_f32_e32 v151, v151
	v_rcp_f32_e32 v152, v152
	v_rcp_f32_e32 v153, v153
	v_lshlrev_b64 v[158:159], 10, v[156:157]
	v_cvt_f32_ubyte3_e32 v161, v137
	v_cvt_f32_ubyte2_e32 v160, v137
	v_cvt_f32_ubyte1_e32 v163, v137
	v_cvt_f32_ubyte0_e32 v162, v137
	v_lshl_add_u64 v[158:159], s[74:75], 0, v[158:159]
	v_cvt_f32_ubyte3_e32 v165, v166
	v_cvt_f32_ubyte2_e32 v164, v166
	v_cvt_f32_ubyte1_e32 v167, v166
	v_cvt_f32_ubyte0_e32 v166, v166
	v_pk_mul_f32 v[162:163], v[118:119], v[162:163]
	v_pk_mul_f32 v[160:161], v[120:121], v[160:161]
	global_store_dwordx4 v[130:131], v[138:141], off
	v_lshl_add_u64 v[158:159], v[158:159], 0, v[134:135]
	v_pk_mul_f32 v[166:167], v[114:115], v[166:167]
	v_pk_mul_f32 v[164:165], v[116:117], v[164:165]
	v_lshl_add_u64 v[158:159], v[158:159], 0, v[194:195]
	v_lshlrev_b64 v[156:157], 11, v[156:157]
	v_lshl_add_u64 v[156:157], s[10:11], 0, v[156:157]
	s_waitcnt vmcnt(9)
	v_lshlrev_b32_e32 v138, 16, v178
	v_and_b32_e32 v139, 0xffff0000, v178
	v_lshlrev_b32_e32 v140, 16, v179
	v_and_b32_e32 v141, 0xffff0000, v179
	v_lshlrev_b32_e32 v142, 16, v180
	v_and_b32_e32 v143, 0xffff0000, v180
	v_lshlrev_b32_e32 v144, 16, v181
	v_and_b32_e32 v145, 0xffff0000, v181
	v_pk_fma_f32 v[140:141], v[148:149], v[160:161], v[140:141]
	v_pk_fma_f32 v[138:139], v[146:147], v[162:163], v[138:139]
	v_pk_fma_f32 v[144:145], v[152:153], v[164:165], v[144:145]
	v_pk_fma_f32 v[142:143], v[150:151], v[166:167], v[142:143]
	v_cvt_pk_bf16_f32 v138, v138, v139
	v_cvt_pk_bf16_f32 v139, v140, v141
	v_exp_f32_e32 v148, v78
	v_cvt_pk_bf16_f32 v140, v142, v143
	v_cvt_pk_bf16_f32 v141, v144, v145
	global_store_dwordx4 v[154:155], v[138:141], off
	v_add_u32_e32 v250, 0x8000, v250
	global_load_dwordx4 v[170:173], v250, s[74:75]
	v_add_u32_e32 v251, 0x8000, v251
	global_load_dwordx4 v[174:177], v251, s[10:11]
	v_add_u32_e32 v251, 0x8000, v251
	global_load_dwordx4 v[178:181], v251, s[10:11]
	v_exp_f32_e32 v149, v79
	v_lshl_add_u64 v[138:139], v[156:157], 0, v[132:133]
	v_exp_f32_e32 v150, v80
	v_exp_f32_e32 v151, v81
	v_exp_f32_e32 v152, v74
	v_exp_f32_e32 v154, v76
	v_exp_f32_e32 v155, v77
	v_exp_f32_e32 v153, v75
	v_pk_add_f32 v[150:151], v[150:151], 1.0 op_sel_hi:[1,0]
	v_pk_add_f32 v[148:149], v[148:149], 1.0 op_sel_hi:[1,0]
	v_pk_add_f32 v[154:155], v[154:155], 1.0 op_sel_hi:[1,0]
	v_pk_add_f32 v[152:153], v[152:153], 1.0 op_sel_hi:[1,0]
	v_rcp_f32_e32 v148, v148
	v_rcp_f32_e32 v149, v149
	v_rcp_f32_e32 v150, v150
	v_rcp_f32_e32 v151, v151
	v_rcp_f32_e32 v152, v152
	v_rcp_f32_e32 v153, v153
	v_rcp_f32_e32 v154, v154
	v_rcp_f32_e32 v155, v155
	v_add_co_u32_e32 v156, vcc, s20, v130
	s_waitcnt vmcnt(12)
	v_mov_b32_e32 v137, v184
	v_mov_b32_e32 v168, v185
	s_nop 0
	v_mov_b32_e32 v140, v182
	s_nop 1
	v_permlane16_swap_b32_e32 v140, v137
	v_mov_b32_e32 v141, v183
	s_nop 1
	v_permlane16_swap_b32_e32 v141, v168
	v_cvt_f32_ubyte3_e32 v161, v140
	v_cvt_f32_ubyte2_e32 v160, v140
	v_cvt_f32_ubyte1_e32 v163, v140
	v_cvt_f32_ubyte0_e32 v162, v140
	v_cvt_f32_ubyte3_e32 v165, v141
	v_cvt_f32_ubyte2_e32 v164, v141
	v_cvt_f32_ubyte1_e32 v167, v141
	v_cvt_f32_ubyte0_e32 v166, v141
	s_waitcnt vmcnt(11)
	v_lshlrev_b32_e32 v142, 16, v186
	v_and_b32_e32 v143, 0xffff0000, v186
	v_lshlrev_b32_e32 v144, 16, v187
	v_and_b32_e32 v145, 0xffff0000, v187
	v_lshlrev_b32_e32 v158, 16, v188
	v_and_b32_e32 v159, 0xffff0000, v188
	v_lshlrev_b32_e32 v146, 16, v189
	v_and_b32_e32 v147, 0xffff0000, v189
	v_pk_mul_f32 v[140:141], v[110:111], v[162:163]
	v_pk_mul_f32 v[160:161], v[112:113], v[160:161]
	v_pk_mul_f32 v[162:163], v[106:107], v[166:167]
	v_pk_mul_f32 v[164:165], v[108:109], v[164:165]
	v_addc_co_u32_e32 v157, vcc, 0, v131, vcc
	v_pk_fma_f32 v[144:145], v[150:151], v[160:161], v[144:145]
	v_pk_fma_f32 v[140:141], v[148:149], v[140:141], v[142:143]
	v_pk_fma_f32 v[146:147], v[154:155], v[164:165], v[146:147]
	v_pk_fma_f32 v[142:143], v[152:153], v[162:163], v[158:159]
	v_cvt_pk_bf16_f32 v140, v140, v141
	v_cvt_pk_bf16_f32 v141, v144, v145
	v_exp_f32_e32 v148, v70
	v_cvt_pk_bf16_f32 v142, v142, v143
	v_cvt_pk_bf16_f32 v143, v146, v147
	v_exp_f32_e32 v149, v71
	v_exp_f32_e32 v150, v72
	v_exp_f32_e32 v151, v73
	v_exp_f32_e32 v152, v66
	v_exp_f32_e32 v153, v67
	v_exp_f32_e32 v154, v68
	v_exp_f32_e32 v155, v69
	v_pk_add_f32 v[150:151], v[150:151], 1.0 op_sel_hi:[1,0]
	v_pk_add_f32 v[148:149], v[148:149], 1.0 op_sel_hi:[1,0]
	v_add_u32_e32 v158, 0x80, v136
	v_pk_add_f32 v[154:155], v[154:155], 1.0 op_sel_hi:[1,0]
	v_pk_add_f32 v[152:153], v[152:153], 1.0 op_sel_hi:[1,0]
	v_rcp_f32_e32 v148, v148
	v_rcp_f32_e32 v149, v149
	v_rcp_f32_e32 v150, v150
	v_rcp_f32_e32 v151, v151
	v_ashrrev_i32_e32 v159, 31, v158
	v_rcp_f32_e32 v152, v152
	v_rcp_f32_e32 v153, v153
	v_rcp_f32_e32 v154, v154
	v_rcp_f32_e32 v155, v155
	v_lshlrev_b64 v[160:161], 10, v[158:159]
	v_cvt_f32_ubyte3_e32 v163, v137
	v_cvt_f32_ubyte2_e32 v162, v137
	v_cvt_f32_ubyte1_e32 v165, v137
	v_cvt_f32_ubyte0_e32 v164, v137
	v_lshl_add_u64 v[160:161], s[74:75], 0, v[160:161]
	v_cvt_f32_ubyte3_e32 v167, v168
	v_cvt_f32_ubyte2_e32 v166, v168
	v_cvt_f32_ubyte1_e32 v169, v168
	v_cvt_f32_ubyte0_e32 v168, v168
	v_pk_mul_f32 v[164:165], v[102:103], v[164:165]
	v_pk_mul_f32 v[162:163], v[104:105], v[162:163]
	global_store_dwordx4 v[138:139], v[140:143], off
	v_lshl_add_u64 v[160:161], v[160:161], 0, v[134:135]
	v_pk_mul_f32 v[168:169], v[98:99], v[168:169]
	v_pk_mul_f32 v[166:167], v[100:101], v[166:167]
	v_lshl_add_u64 v[160:161], v[160:161], 0, v[194:195]
	v_lshlrev_b64 v[158:159], 11, v[158:159]
	v_lshl_add_u64 v[158:159], s[10:11], 0, v[158:159]
	v_add_u32_e32 v136, 0xa0, v136
	v_ashrrev_i32_e32 v137, 31, v136
	s_waitcnt vmcnt(11)
	v_lshlrev_b32_e32 v138, 16, v190
	v_and_b32_e32 v139, 0xffff0000, v190
	v_lshlrev_b32_e32 v140, 16, v191
	v_and_b32_e32 v141, 0xffff0000, v191
	v_lshlrev_b32_e32 v142, 16, v192
	v_and_b32_e32 v143, 0xffff0000, v192
	v_lshlrev_b32_e32 v144, 16, v193
	v_and_b32_e32 v145, 0xffff0000, v193
	v_pk_fma_f32 v[140:141], v[150:151], v[162:163], v[140:141]
	v_pk_fma_f32 v[138:139], v[148:149], v[164:165], v[138:139]
	v_pk_fma_f32 v[144:145], v[154:155], v[166:167], v[144:145]
	v_pk_fma_f32 v[142:143], v[152:153], v[168:169], v[142:143]
	v_cvt_pk_bf16_f32 v138, v138, v139
	v_cvt_pk_bf16_f32 v139, v140, v141
	v_exp_f32_e32 v148, v30
	v_cvt_pk_bf16_f32 v140, v142, v143
	v_cvt_pk_bf16_f32 v141, v144, v145
	global_store_dwordx4 v[156:157], v[138:141], off
	v_exp_f32_e32 v149, v31
	v_lshl_add_u64 v[138:139], v[158:159], 0, v[132:133]
	v_exp_f32_e32 v150, v32
	v_exp_f32_e32 v151, v33
	v_exp_f32_e32 v152, v26
	v_exp_f32_e32 v154, v28
	v_exp_f32_e32 v155, v29
	v_exp_f32_e32 v153, v27
	v_pk_add_f32 v[150:151], v[150:151], 1.0 op_sel_hi:[1,0]
	v_pk_add_f32 v[148:149], v[148:149], 1.0 op_sel_hi:[1,0]
	v_pk_add_f32 v[154:155], v[154:155], 1.0 op_sel_hi:[1,0]
	v_pk_add_f32 v[152:153], v[152:153], 1.0 op_sel_hi:[1,0]
	v_rcp_f32_e32 v148, v148
	v_rcp_f32_e32 v149, v149
	v_rcp_f32_e32 v150, v150
	v_rcp_f32_e32 v151, v151
	v_rcp_f32_e32 v152, v152
	v_rcp_f32_e32 v153, v153
	v_rcp_f32_e32 v154, v154
	v_rcp_f32_e32 v155, v155
	v_add_co_u32_e32 v156, vcc, s48, v130
	s_waitcnt vmcnt(11)
	v_mov_b32_e32 v168, v240
	v_mov_b32_e32 v169, v241
	s_nop 0
	v_mov_b32_e32 v140, v238
	s_nop 1
	v_permlane16_swap_b32_e32 v140, v168
	v_mov_b32_e32 v141, v239
	s_nop 1
	v_permlane16_swap_b32_e32 v141, v169
	v_cvt_f32_ubyte3_e32 v161, v140
	v_cvt_f32_ubyte2_e32 v160, v140
	v_cvt_f32_ubyte1_e32 v163, v140
	v_cvt_f32_ubyte0_e32 v162, v140
	v_cvt_f32_ubyte3_e32 v165, v141
	v_cvt_f32_ubyte2_e32 v164, v141
	v_cvt_f32_ubyte1_e32 v167, v141
	v_cvt_f32_ubyte0_e32 v166, v141
	s_waitcnt vmcnt(10)
	v_lshlrev_b32_e32 v142, 16, v242
	v_and_b32_e32 v143, 0xffff0000, v242
	v_lshlrev_b32_e32 v144, 16, v243
	v_and_b32_e32 v145, 0xffff0000, v243
	v_lshlrev_b32_e32 v158, 16, v244
	v_and_b32_e32 v159, 0xffff0000, v244
	v_lshlrev_b32_e32 v146, 16, v245
	v_and_b32_e32 v147, 0xffff0000, v245
	v_pk_mul_f32 v[140:141], v[62:63], v[162:163]
	v_pk_mul_f32 v[160:161], v[64:65], v[160:161]
	v_pk_mul_f32 v[162:163], v[58:59], v[166:167]
	v_pk_mul_f32 v[164:165], v[60:61], v[164:165]
	v_addc_co_u32_e32 v157, vcc, 0, v131, vcc
	v_pk_fma_f32 v[144:145], v[150:151], v[160:161], v[144:145]
	v_pk_fma_f32 v[140:141], v[148:149], v[140:141], v[142:143]
	v_pk_fma_f32 v[146:147], v[154:155], v[164:165], v[146:147]
	v_pk_fma_f32 v[142:143], v[152:153], v[162:163], v[158:159]
	v_cvt_pk_bf16_f32 v140, v140, v141
	v_cvt_pk_bf16_f32 v141, v144, v145
	v_exp_f32_e32 v148, v22
	v_cvt_pk_bf16_f32 v142, v142, v143
	v_cvt_pk_bf16_f32 v143, v146, v147
	v_exp_f32_e32 v149, v23
	v_exp_f32_e32 v150, v24
	v_exp_f32_e32 v151, v25
	v_exp_f32_e32 v152, v18
	v_exp_f32_e32 v153, v19
	v_exp_f32_e32 v154, v20
	v_exp_f32_e32 v155, v21
	v_pk_add_f32 v[150:151], v[150:151], 1.0 op_sel_hi:[1,0]
	v_pk_add_f32 v[148:149], v[148:149], 1.0 op_sel_hi:[1,0]
	v_pk_add_f32 v[152:153], v[152:153], 1.0 op_sel_hi:[1,0]
	v_lshlrev_b64 v[158:159], 10, v[136:137]
	v_pk_add_f32 v[154:155], v[154:155], 1.0 op_sel_hi:[1,0]
	v_rcp_f32_e32 v148, v148
	v_rcp_f32_e32 v149, v149
	v_rcp_f32_e32 v150, v150
	v_rcp_f32_e32 v151, v151
	v_rcp_f32_e32 v152, v152
	v_rcp_f32_e32 v153, v153
	v_lshl_add_u64 v[158:159], s[74:75], 0, v[158:159]
	v_rcp_f32_e32 v154, v154
	v_rcp_f32_e32 v155, v155
	v_lshlrev_b64 v[136:137], 11, v[136:137]
	v_lshl_add_u64 v[134:135], v[158:159], 0, v[134:135]
	v_lshl_add_u64 v[160:161], s[10:11], 0, v[136:137]
	v_lshl_add_u64 v[158:159], v[134:135], 0, v[194:195]
	v_cvt_f32_ubyte3_e32 v135, v168
	v_cvt_f32_ubyte2_e32 v134, v168
	v_cvt_f32_ubyte1_e32 v137, v168
	v_cvt_f32_ubyte0_e32 v136, v168
	v_cvt_f32_ubyte1_e32 v165, v169
	v_cvt_f32_ubyte0_e32 v164, v169
	v_cvt_f32_ubyte3_e32 v163, v169
	v_cvt_f32_ubyte2_e32 v162, v169
	v_pk_mul_f32 v[136:137], v[54:55], v[136:137]
	v_pk_mul_f32 v[134:135], v[56:57], v[134:135]
	v_pk_mul_f32 v[164:165], v[50:51], v[164:165]
	global_store_dwordx4 v[138:139], v[140:143], off
	v_pk_mul_f32 v[162:163], v[52:53], v[162:163]
	s_waitcnt vmcnt(10)
	v_lshlrev_b32_e32 v138, 16, v246
	v_and_b32_e32 v139, 0xffff0000, v246
	v_lshlrev_b32_e32 v140, 16, v247
	v_and_b32_e32 v141, 0xffff0000, v247
	v_lshlrev_b32_e32 v142, 16, v248
	v_and_b32_e32 v143, 0xffff0000, v248
	v_lshlrev_b32_e32 v144, 16, v249
	v_and_b32_e32 v145, 0xffff0000, v249
	v_pk_fma_f32 v[140:141], v[150:151], v[134:135], v[140:141]
	v_pk_fma_f32 v[134:135], v[148:149], v[136:137], v[138:139]
	v_pk_fma_f32 v[136:137], v[152:153], v[164:165], v[142:143]
	v_pk_fma_f32 v[138:139], v[154:155], v[162:163], v[144:145]
	v_cvt_pk_bf16_f32 v134, v134, v135
	v_cvt_pk_bf16_f32 v135, v140, v141
	v_cvt_pk_bf16_f32 v136, v136, v137
	v_lshl_add_u64 v[142:143], v[160:161], 0, v[132:133]
	v_cvt_pk_bf16_f32 v137, v138, v139
	global_store_dwordx4 v[156:157], v[134:137], off
	v_exp_f32_e32 v132, v14
	v_exp_f32_e32 v133, v15
	v_exp_f32_e32 v144, v16
	v_exp_f32_e32 v145, v17
	v_exp_f32_e32 v146, v10
	v_exp_f32_e32 v148, v12
	v_exp_f32_e32 v149, v13
	v_exp_f32_e32 v147, v11
	v_pk_add_f32 v[144:145], v[144:145], 1.0 op_sel_hi:[1,0]
	v_pk_add_f32 v[132:133], v[132:133], 1.0 op_sel_hi:[1,0]
	v_pk_add_f32 v[148:149], v[148:149], 1.0 op_sel_hi:[1,0]
	v_pk_add_f32 v[146:147], v[146:147], 1.0 op_sel_hi:[1,0]
	v_rcp_f32_e32 v132, v132
	v_rcp_f32_e32 v133, v133
	v_rcp_f32_e32 v144, v144
	v_rcp_f32_e32 v145, v145
	v_rcp_f32_e32 v146, v146
	v_rcp_f32_e32 v147, v147
	v_rcp_f32_e32 v148, v148
	v_rcp_f32_e32 v149, v149
	v_add_co_u32_e32 v150, vcc, s49, v130
	s_waitcnt vmcnt(6)
	v_mov_b32_e32 v160, v172
	v_mov_b32_e32 v161, v173
	s_nop 0
	v_mov_b32_e32 v134, v170
	s_nop 1
	v_permlane16_swap_b32_e32 v134, v160
	v_mov_b32_e32 v135, v171
	s_nop 1
	v_permlane16_swap_b32_e32 v135, v161
	v_cvt_f32_ubyte3_e32 v153, v134
	v_cvt_f32_ubyte2_e32 v152, v134
	v_cvt_f32_ubyte1_e32 v155, v134
	v_cvt_f32_ubyte0_e32 v154, v134
	v_cvt_f32_ubyte3_e32 v157, v135
	v_cvt_f32_ubyte2_e32 v156, v135
	v_cvt_f32_ubyte1_e32 v159, v135
	v_cvt_f32_ubyte0_e32 v158, v135
	v_addc_co_u32_e32 v151, vcc, 0, v131, vcc
	s_waitcnt vmcnt(5)
	v_lshlrev_b32_e32 v130, 16, v174
	v_and_b32_e32 v131, 0xffff0000, v174
	v_lshlrev_b32_e32 v136, 16, v175
	v_and_b32_e32 v137, 0xffff0000, v175
	v_lshlrev_b32_e32 v138, 16, v176
	v_and_b32_e32 v139, 0xffff0000, v176
	v_lshlrev_b32_e32 v140, 16, v177
	v_and_b32_e32 v141, 0xffff0000, v177
	v_pk_mul_f32 v[134:135], v[46:47], v[154:155]
	v_pk_mul_f32 v[152:153], v[48:49], v[152:153]
	v_pk_mul_f32 v[154:155], v[42:43], v[158:159]
	v_pk_mul_f32 v[156:157], v[44:45], v[156:157]
	v_pk_fma_f32 v[136:137], v[144:145], v[152:153], v[136:137]
	v_pk_fma_f32 v[130:131], v[132:133], v[134:135], v[130:131]
	v_pk_fma_f32 v[134:135], v[148:149], v[156:157], v[140:141]
	v_pk_fma_f32 v[132:133], v[146:147], v[154:155], v[138:139]
	v_cvt_pk_bf16_f32 v130, v130, v131
	v_cvt_pk_bf16_f32 v131, v136, v137
	v_exp_f32_e32 v138, v6
	v_cvt_pk_bf16_f32 v132, v132, v133
	v_cvt_pk_bf16_f32 v133, v134, v135
	v_exp_f32_e32 v139, v7
	v_exp_f32_e32 v140, v8
	v_exp_f32_e32 v141, v9
	v_exp_f32_e32 v144, v2
	v_exp_f32_e32 v146, v4
	v_exp_f32_e32 v147, v5
	v_exp_f32_e32 v145, v3
	v_pk_add_f32 v[140:141], v[140:141], 1.0 op_sel_hi:[1,0]
	v_pk_add_f32 v[138:139], v[138:139], 1.0 op_sel_hi:[1,0]
	v_pk_add_f32 v[146:147], v[146:147], 1.0 op_sel_hi:[1,0]
	v_pk_add_f32 v[144:145], v[144:145], 1.0 op_sel_hi:[1,0]
	v_rcp_f32_e32 v138, v138
	v_rcp_f32_e32 v139, v139
	v_rcp_f32_e32 v140, v140
	v_rcp_f32_e32 v141, v141
	v_rcp_f32_e32 v144, v144
	v_rcp_f32_e32 v145, v145
	v_rcp_f32_e32 v146, v146
	v_rcp_f32_e32 v147, v147
	v_cvt_f32_ubyte3_e32 v149, v160
	v_cvt_f32_ubyte2_e32 v148, v160
	v_cvt_f32_ubyte1_e32 v153, v160
	v_cvt_f32_ubyte0_e32 v152, v160
	v_cvt_f32_ubyte3_e32 v155, v161
	v_cvt_f32_ubyte2_e32 v154, v161
	v_cvt_f32_ubyte1_e32 v157, v161
	v_cvt_f32_ubyte0_e32 v156, v161
	v_pk_mul_f32 v[152:153], v[38:39], v[152:153]
	v_pk_mul_f32 v[148:149], v[40:41], v[148:149]
	global_store_dwordx4 v[142:143], v[130:133], off
	v_pk_mul_f32 v[156:157], v[34:35], v[156:157]
	v_pk_mul_f32 v[154:155], v[36:37], v[154:155]
	s_waitcnt vmcnt(5)
	v_lshlrev_b32_e32 v130, 16, v178
	v_and_b32_e32 v131, 0xffff0000, v178
	v_lshlrev_b32_e32 v132, 16, v179
	v_and_b32_e32 v133, 0xffff0000, v179
	v_lshlrev_b32_e32 v134, 16, v180
	v_and_b32_e32 v135, 0xffff0000, v180
	v_lshlrev_b32_e32 v136, 16, v181
	v_and_b32_e32 v137, 0xffff0000, v181
	v_pk_fma_f32 v[132:133], v[140:141], v[148:149], v[132:133]
	v_pk_fma_f32 v[130:131], v[138:139], v[152:153], v[130:131]
	v_pk_fma_f32 v[136:137], v[146:147], v[154:155], v[136:137]
	v_pk_fma_f32 v[134:135], v[144:145], v[156:157], v[134:135]
	v_cvt_pk_bf16_f32 v130, v130, v131
	v_cvt_pk_bf16_f32 v131, v132, v133
	s_nop 0
	v_cvt_pk_bf16_f32 v132, v134, v135
	v_cvt_pk_bf16_f32 v133, v136, v137
	global_store_dwordx4 v[150:151], v[130:133], off
	s_cbranch_execz .LBB0_553

.LBB0_553:
	s_nop 0
	v_mov_b32_e32 v131, v207
	v_mov_b32_e32 v133, v208
	s_lshl_b32 s20, s57, 8
	s_or_b32 s20, s20, s35
	v_lshl_add_u32 v130, v133, 3, s20
	v_add_u32_e32 v132, s4, v131
	v_and_b32_e32 v133, 1, v133
	v_cmp_eq_u32_e32 vcc, 1, v133
	v_ashrrev_i32_e32 v133, 31, v132
	v_ashrrev_i32_e32 v131, 31, v130
	v_lshlrev_b64 v[132:133], 10, v[132:133]
	v_lshl_add_u64 v[130:131], v[132:133], 0, v[130:131]
	v_cndmask_b32_e32 v194, 0, v221, vcc
	v_lshl_add_u64 v[132:133], s[76:77], 0, v[130:131]
	v_lshl_add_u64 v[136:137], v[132:133], 0, v[194:195]
	v_add_u32_e32 v190, v130, v194
	global_load_dwordx4 v[158:161], v190, s[76:77]
	global_load_dwordx4 v[162:165], v190, s[76:77] offset:128
	v_add_u32_e32 v190, 0x8000, v190
	global_load_dwordx4 v[166:169], v190, s[76:77]
	global_load_dwordx4 v[170:173], v190, s[76:77] offset:128
	v_add_u32_e32 v190, 0x18000, v190
	global_load_dwordx4 v[174:177], v190, s[76:77]
	global_load_dwordx4 v[178:181], v190, s[76:77] offset:128
	v_add_u32_e32 v190, 0x8000, v190
	global_load_dwordx4 v[182:185], v190, s[76:77]
	global_load_dwordx4 v[186:189], v190, s[76:77] offset:128
	s_mov_b32 s99, s4
	s_mov_b32 s4, s70
	s_mov_b32 m0, s43
	s_nop 0
	buffer_load_dwordx4 v253, s[4:7], s98 offen lds
	s_mov_b32 m0, s44
	s_nop 0
	buffer_load_dwordx4 v254, s[4:7], s98 offen lds
	s_mov_b32 s4, s99
	v_lshl_add_u64 v[138:139], v[130:131], 1, s[10:11]
	v_add_co_u32_e32 v140, vcc, s42, v138
	s_waitcnt vmcnt(9)
	v_mov_b32_e32 v148, v160
	v_mov_b32_e32 v152, v161
	s_nop 0
	v_mov_b32_e32 v132, v158
	s_nop 1
	v_permlane16_swap_b32_e32 v132, v148
	v_mov_b32_e32 v133, v159
	s_nop 1
	v_permlane16_swap_b32_e32 v133, v152
	v_cvt_f32_ubyte1_e32 v135, v132
	v_cvt_f32_ubyte0_e32 v134, v132
	v_cvt_f32_ubyte3_e32 v143, v132
	v_cvt_f32_ubyte2_e32 v142, v132
	v_cvt_f32_ubyte1_e32 v145, v133
	v_cvt_f32_ubyte0_e32 v144, v133
	v_cvt_f32_ubyte3_e32 v147, v133
	v_cvt_f32_ubyte2_e32 v146, v133
	v_cvt_f32_ubyte1_e32 v133, v148
	v_cvt_f32_ubyte0_e32 v132, v148
	v_pk_mul_f32 v[134:135], v[126:127], v[134:135]
	v_addc_co_u32_e32 v141, vcc, 0, v139, vcc
	v_cvt_f32_ubyte3_e32 v149, v148
	v_cvt_f32_ubyte2_e32 v148, v148
	v_cvt_f32_ubyte1_e32 v151, v152
	v_cvt_f32_ubyte0_e32 v150, v152
	v_cvt_f32_ubyte3_e32 v153, v152
	v_cvt_f32_ubyte2_e32 v152, v152
	v_pk_mul_f32 v[142:143], v[128:129], v[142:143]
	v_pk_mul_f32 v[146:147], v[124:125], v[146:147]
	v_pk_mul_f32 v[144:145], v[122:123], v[144:145]
	v_pk_mul_f32 v[154:155], v[118:119], v[132:133]
	v_cvt_pk_bf16_f32 v132, v134, v135
	v_cvt_pk_bf16_f32 v133, v142, v143
	v_cvt_pk_bf16_f32 v134, v144, v145
	v_cvt_pk_bf16_f32 v135, v146, v147
	v_pk_mul_f32 v[148:149], v[120:121], v[148:149]
	v_pk_mul_f32 v[152:153], v[116:117], v[152:153]
	v_pk_mul_f32 v[150:151], v[114:115], v[150:151]
	global_store_dwordx4 v[138:139], v[132:135], off
	s_nop 1
	v_cvt_pk_bf16_f32 v132, v154, v155
	v_cvt_pk_bf16_f32 v133, v148, v149
	v_cvt_pk_bf16_f32 v134, v150, v151
	v_cvt_pk_bf16_f32 v135, v152, v153
	global_store_dwordx4 v[140:141], v[132:135], off
	v_lshl_add_u64 v[136:137], v[130:131], 0, s[14:15]
	v_lshl_add_u64 v[142:143], s[76:77], 0, v[136:137]
	v_lshl_add_u64 v[142:143], v[142:143], 0, v[194:195]
	v_lshl_add_u64 v[136:137], v[136:137], 1, s[10:11]
	s_waitcnt vmcnt(10)
	v_mov_b32_e32 v150, v164
	v_mov_b32_e32 v154, v165
	s_nop 0
	v_mov_b32_e32 v132, v162
	s_nop 1
	v_permlane16_swap_b32_e32 v132, v150
	v_mov_b32_e32 v133, v163
	s_nop 1
	v_permlane16_swap_b32_e32 v133, v154
	v_cvt_f32_ubyte1_e32 v135, v132
	v_cvt_f32_ubyte0_e32 v134, v132
	v_cvt_f32_ubyte3_e32 v145, v132
	v_cvt_f32_ubyte2_e32 v144, v132
	v_cvt_f32_ubyte1_e32 v147, v133
	v_cvt_f32_ubyte0_e32 v146, v133
	v_cvt_f32_ubyte3_e32 v149, v133
	v_cvt_f32_ubyte2_e32 v148, v133
	v_cvt_f32_ubyte1_e32 v133, v150
	v_cvt_f32_ubyte0_e32 v132, v150
	v_pk_mul_f32 v[134:135], v[94:95], v[134:135]
	v_cvt_f32_ubyte3_e32 v151, v150
	v_cvt_f32_ubyte2_e32 v150, v150
	v_cvt_f32_ubyte1_e32 v153, v154
	v_cvt_f32_ubyte0_e32 v152, v154
	v_cvt_f32_ubyte3_e32 v155, v154
	v_cvt_f32_ubyte2_e32 v154, v154
	v_pk_mul_f32 v[144:145], v[96:97], v[144:145]
	v_pk_mul_f32 v[148:149], v[92:93], v[148:149]
	v_pk_mul_f32 v[146:147], v[90:91], v[146:147]
	v_pk_mul_f32 v[156:157], v[86:87], v[132:133]
	v_cvt_pk_bf16_f32 v132, v134, v135
	v_cvt_pk_bf16_f32 v133, v144, v145
	v_cvt_pk_bf16_f32 v134, v146, v147
	v_cvt_pk_bf16_f32 v135, v148, v149
	v_pk_mul_f32 v[150:151], v[88:89], v[150:151]
	v_pk_mul_f32 v[154:155], v[84:85], v[154:155]
	v_pk_mul_f32 v[152:153], v[82:83], v[152:153]
	global_store_dwordx4 v[138:139], v[132:135], off offset:256
	v_add_co_u32_e32 v138, vcc, s42, v136
	s_nop 0
	v_cvt_pk_bf16_f32 v132, v156, v157
	v_cvt_pk_bf16_f32 v133, v150, v151
	v_cvt_pk_bf16_f32 v134, v152, v153
	v_cvt_pk_bf16_f32 v135, v154, v155
	global_store_dwordx4 v[140:141], v[132:135], off offset:256
	v_addc_co_u32_e32 v139, vcc, 0, v137, vcc
	s_waitcnt vmcnt(11)
	v_mov_b32_e32 v148, v168
	v_mov_b32_e32 v152, v169
	s_nop 0
	v_mov_b32_e32 v132, v166
	s_nop 1
	v_permlane16_swap_b32_e32 v132, v148
	v_mov_b32_e32 v133, v167
	s_nop 1
	v_permlane16_swap_b32_e32 v133, v152
	v_cvt_f32_ubyte1_e32 v135, v132
	v_cvt_f32_ubyte0_e32 v134, v132
	v_cvt_f32_ubyte3_e32 v141, v132
	v_cvt_f32_ubyte2_e32 v140, v132
	v_cvt_f32_ubyte1_e32 v145, v133
	v_cvt_f32_ubyte0_e32 v144, v133
	v_cvt_f32_ubyte3_e32 v147, v133
	v_cvt_f32_ubyte2_e32 v146, v133
	v_cvt_f32_ubyte1_e32 v133, v148
	v_cvt_f32_ubyte0_e32 v132, v148
	v_pk_mul_f32 v[134:135], v[110:111], v[134:135]
	v_cvt_f32_ubyte3_e32 v149, v148
	v_cvt_f32_ubyte2_e32 v148, v148
	v_cvt_f32_ubyte1_e32 v151, v152
	v_cvt_f32_ubyte0_e32 v150, v152
	v_cvt_f32_ubyte3_e32 v153, v152
	v_cvt_f32_ubyte2_e32 v152, v152
	v_pk_mul_f32 v[140:141], v[112:113], v[140:141]
	v_pk_mul_f32 v[146:147], v[108:109], v[146:147]
	v_pk_mul_f32 v[144:145], v[106:107], v[144:145]
	v_pk_mul_f32 v[154:155], v[102:103], v[132:133]
	v_cvt_pk_bf16_f32 v132, v134, v135
	v_cvt_pk_bf16_f32 v133, v140, v141
	v_cvt_pk_bf16_f32 v134, v144, v145
	v_cvt_pk_bf16_f32 v135, v146, v147
	v_pk_mul_f32 v[148:149], v[104:105], v[148:149]
	v_pk_mul_f32 v[152:153], v[100:101], v[152:153]
	v_pk_mul_f32 v[150:151], v[98:99], v[150:151]
	global_store_dwordx4 v[136:137], v[132:135], off
	v_lshl_add_u64 v[140:141], v[130:131], 0, s[16:17]
	s_nop 0
	v_cvt_pk_bf16_f32 v132, v154, v155
	v_cvt_pk_bf16_f32 v133, v148, v149
	v_cvt_pk_bf16_f32 v134, v150, v151
	v_cvt_pk_bf16_f32 v135, v152, v153
	global_store_dwordx4 v[138:139], v[132:135], off
	v_lshl_add_u64 v[142:143], s[76:77], 0, v[140:141]
	v_lshl_add_u64 v[142:143], v[142:143], 0, v[194:195]
	s_waitcnt vmcnt(12)
	v_mov_b32_e32 v150, v172
	v_mov_b32_e32 v154, v173
	s_nop 0
	v_mov_b32_e32 v132, v170
	s_nop 1
	v_permlane16_swap_b32_e32 v132, v150
	v_mov_b32_e32 v133, v171
	s_nop 1
	v_permlane16_swap_b32_e32 v133, v154
	v_cvt_f32_ubyte1_e32 v135, v132
	v_cvt_f32_ubyte0_e32 v134, v132
	v_cvt_f32_ubyte3_e32 v145, v132
	v_cvt_f32_ubyte2_e32 v144, v132
	v_cvt_f32_ubyte1_e32 v147, v133
	v_cvt_f32_ubyte0_e32 v146, v133
	v_cvt_f32_ubyte3_e32 v149, v133
	v_cvt_f32_ubyte2_e32 v148, v133
	v_cvt_f32_ubyte1_e32 v133, v150
	v_cvt_f32_ubyte0_e32 v132, v150
	v_pk_mul_f32 v[134:135], v[78:79], v[134:135]
	v_cvt_f32_ubyte3_e32 v151, v150
	v_cvt_f32_ubyte2_e32 v150, v150
	v_cvt_f32_ubyte1_e32 v153, v154
	v_cvt_f32_ubyte0_e32 v152, v154
	v_cvt_f32_ubyte3_e32 v155, v154
	v_cvt_f32_ubyte2_e32 v154, v154
	v_pk_mul_f32 v[144:145], v[80:81], v[144:145]
	v_pk_mul_f32 v[148:149], v[76:77], v[148:149]
	v_pk_mul_f32 v[146:147], v[74:75], v[146:147]
	v_pk_mul_f32 v[156:157], v[70:71], v[132:133]
	v_cvt_pk_bf16_f32 v132, v134, v135
	v_cvt_pk_bf16_f32 v133, v144, v145
	v_cvt_pk_bf16_f32 v134, v146, v147
	v_cvt_pk_bf16_f32 v135, v148, v149
	v_pk_mul_f32 v[150:151], v[72:73], v[150:151]
	v_pk_mul_f32 v[154:155], v[68:69], v[154:155]
	v_pk_mul_f32 v[152:153], v[66:67], v[152:153]
	global_store_dwordx4 v[136:137], v[132:135], off offset:256
	v_lshl_add_u64 v[136:137], v[140:141], 1, s[10:11]
	s_nop 0
	v_cvt_pk_bf16_f32 v132, v156, v157
	v_cvt_pk_bf16_f32 v133, v150, v151
	v_cvt_pk_bf16_f32 v134, v152, v153
	v_cvt_pk_bf16_f32 v135, v154, v155
	global_store_dwordx4 v[138:139], v[132:135], off offset:256
	v_add_co_u32_e32 v138, vcc, s42, v136
	s_waitcnt vmcnt(13)
	v_mov_b32_e32 v148, v176
	v_mov_b32_e32 v152, v177
	s_nop 0
	v_mov_b32_e32 v132, v174
	s_nop 1
	v_permlane16_swap_b32_e32 v132, v148
	v_mov_b32_e32 v133, v175
	s_nop 1
	v_permlane16_swap_b32_e32 v133, v152
	v_cvt_f32_ubyte1_e32 v135, v132
	v_cvt_f32_ubyte0_e32 v134, v132
	v_cvt_f32_ubyte3_e32 v141, v132
	v_cvt_f32_ubyte2_e32 v140, v132
	v_cvt_f32_ubyte1_e32 v145, v133
	v_cvt_f32_ubyte0_e32 v144, v133
	v_cvt_f32_ubyte3_e32 v147, v133
	v_cvt_f32_ubyte2_e32 v146, v133
	v_cvt_f32_ubyte1_e32 v133, v148
	v_cvt_f32_ubyte0_e32 v132, v148
	v_pk_mul_f32 v[134:135], v[62:63], v[134:135]
	v_addc_co_u32_e32 v139, vcc, 0, v137, vcc
	v_cvt_f32_ubyte3_e32 v149, v148
	v_cvt_f32_ubyte2_e32 v148, v148
	v_cvt_f32_ubyte1_e32 v151, v152
	v_cvt_f32_ubyte0_e32 v150, v152
	v_cvt_f32_ubyte3_e32 v153, v152
	v_cvt_f32_ubyte2_e32 v152, v152
	v_pk_mul_f32 v[140:141], v[64:65], v[140:141]
	v_pk_mul_f32 v[146:147], v[60:61], v[146:147]
	v_pk_mul_f32 v[144:145], v[58:59], v[144:145]
	v_pk_mul_f32 v[154:155], v[54:55], v[132:133]
	v_cvt_pk_bf16_f32 v132, v134, v135
	v_cvt_pk_bf16_f32 v133, v140, v141
	v_cvt_pk_bf16_f32 v134, v144, v145
	v_cvt_pk_bf16_f32 v135, v146, v147
	v_pk_mul_f32 v[148:149], v[56:57], v[148:149]
	v_pk_mul_f32 v[152:153], v[52:53], v[152:153]
	v_pk_mul_f32 v[150:151], v[50:51], v[150:151]
	global_store_dwordx4 v[136:137], v[132:135], off
	v_lshl_add_u64 v[140:141], v[130:131], 0, s[18:19]
	v_lshl_add_u64 v[130:131], s[76:77], 0, v[140:141]
	v_cvt_pk_bf16_f32 v132, v154, v155
	v_cvt_pk_bf16_f32 v133, v148, v149
	v_cvt_pk_bf16_f32 v134, v150, v151
	v_cvt_pk_bf16_f32 v135, v152, v153
	global_store_dwordx4 v[138:139], v[132:135], off
	v_lshl_add_u64 v[142:143], v[130:131], 0, v[194:195]
	s_waitcnt vmcnt(14)
	v_mov_b32_e32 v148, v180
	v_mov_b32_e32 v152, v181
	s_nop 0
	v_mov_b32_e32 v132, v178
	s_nop 1
	v_permlane16_swap_b32_e32 v132, v148
	v_mov_b32_e32 v133, v179
	s_nop 1
	v_permlane16_swap_b32_e32 v133, v152
	v_cvt_f32_ubyte1_e32 v131, v132
	v_cvt_f32_ubyte0_e32 v130, v132
	v_cvt_f32_ubyte3_e32 v135, v132
	v_cvt_f32_ubyte2_e32 v134, v132
	v_cvt_f32_ubyte1_e32 v145, v133
	v_cvt_f32_ubyte0_e32 v144, v133
	v_cvt_f32_ubyte3_e32 v147, v133
	v_cvt_f32_ubyte2_e32 v146, v133
	v_cvt_f32_ubyte1_e32 v133, v148
	v_cvt_f32_ubyte0_e32 v132, v148
	v_pk_mul_f32 v[130:131], v[30:31], v[130:131]
	v_cvt_f32_ubyte3_e32 v149, v148
	v_cvt_f32_ubyte2_e32 v148, v148
	v_cvt_f32_ubyte1_e32 v151, v152
	v_cvt_f32_ubyte0_e32 v150, v152
	v_cvt_f32_ubyte3_e32 v153, v152
	v_cvt_f32_ubyte2_e32 v152, v152
	v_pk_mul_f32 v[134:135], v[32:33], v[134:135]
	v_pk_mul_f32 v[146:147], v[28:29], v[146:147]
	v_pk_mul_f32 v[144:145], v[26:27], v[144:145]
	v_pk_mul_f32 v[154:155], v[22:23], v[132:133]
	v_cvt_pk_bf16_f32 v130, v130, v131
	v_cvt_pk_bf16_f32 v131, v134, v135
	v_cvt_pk_bf16_f32 v132, v144, v145
	v_cvt_pk_bf16_f32 v133, v146, v147
	v_pk_mul_f32 v[148:149], v[24:25], v[148:149]
	v_pk_mul_f32 v[152:153], v[20:21], v[152:153]
	v_pk_mul_f32 v[150:151], v[18:19], v[150:151]
	global_store_dwordx4 v[136:137], v[130:133], off offset:256
	v_lshl_add_u64 v[134:135], v[140:141], 1, s[10:11]
	v_add_co_u32_e32 v136, vcc, s42, v134
	v_cvt_pk_bf16_f32 v130, v154, v155
	v_cvt_pk_bf16_f32 v131, v148, v149
	v_cvt_pk_bf16_f32 v132, v150, v151
	v_cvt_pk_bf16_f32 v133, v152, v153
	global_store_dwordx4 v[138:139], v[130:133], off offset:256
	v_addc_co_u32_e32 v137, vcc, 0, v135, vcc
	s_waitcnt vmcnt(15)
	v_mov_b32_e32 v146, v184
	v_mov_b32_e32 v150, v185
	s_nop 0
	v_mov_b32_e32 v130, v182
	s_nop 1
	v_permlane16_swap_b32_e32 v130, v146
	v_mov_b32_e32 v131, v183
	s_nop 1
	v_permlane16_swap_b32_e32 v131, v150
	v_cvt_f32_ubyte1_e32 v133, v130
	v_cvt_f32_ubyte0_e32 v132, v130
	v_cvt_f32_ubyte3_e32 v139, v130
	v_cvt_f32_ubyte2_e32 v138, v130
	v_cvt_f32_ubyte1_e32 v141, v131
	v_cvt_f32_ubyte0_e32 v140, v131
	v_cvt_f32_ubyte3_e32 v145, v131
	v_cvt_f32_ubyte2_e32 v144, v131
	v_cvt_f32_ubyte1_e32 v131, v146
	v_cvt_f32_ubyte0_e32 v130, v146
	v_pk_mul_f32 v[132:133], v[46:47], v[132:133]
	v_cvt_f32_ubyte3_e32 v147, v146
	v_cvt_f32_ubyte2_e32 v146, v146
	v_cvt_f32_ubyte1_e32 v149, v150
	v_cvt_f32_ubyte0_e32 v148, v150
	v_cvt_f32_ubyte3_e32 v151, v150
	v_cvt_f32_ubyte2_e32 v150, v150
	v_pk_mul_f32 v[138:139], v[48:49], v[138:139]
	v_pk_mul_f32 v[144:145], v[44:45], v[144:145]
	v_pk_mul_f32 v[140:141], v[42:43], v[140:141]
	v_pk_mul_f32 v[152:153], v[38:39], v[130:131]
	v_cvt_pk_bf16_f32 v130, v132, v133
	v_cvt_pk_bf16_f32 v131, v138, v139
	v_cvt_pk_bf16_f32 v132, v140, v141
	v_cvt_pk_bf16_f32 v133, v144, v145
	v_pk_mul_f32 v[146:147], v[40:41], v[146:147]
	v_pk_mul_f32 v[150:151], v[36:37], v[150:151]
	v_pk_mul_f32 v[148:149], v[34:35], v[148:149]
	global_store_dwordx4 v[134:135], v[130:133], off
	s_nop 1
	v_cvt_pk_bf16_f32 v130, v152, v153
	v_cvt_pk_bf16_f32 v131, v146, v147
	v_cvt_pk_bf16_f32 v132, v148, v149
	v_cvt_pk_bf16_f32 v133, v150, v151
	global_store_dwordx4 v[136:137], v[130:133], off
	s_waitcnt vmcnt(16)
	v_mov_b32_e32 v144, v188
	v_mov_b32_e32 v148, v189
	s_nop 0
	v_mov_b32_e32 v130, v186
	s_nop 1
	v_permlane16_swap_b32_e32 v130, v144
	v_mov_b32_e32 v131, v187
	s_nop 1
	v_permlane16_swap_b32_e32 v131, v148
	v_cvt_f32_ubyte1_e32 v133, v130
	v_cvt_f32_ubyte0_e32 v132, v130
	v_cvt_f32_ubyte3_e32 v139, v130
	v_cvt_f32_ubyte2_e32 v138, v130
	v_cvt_f32_ubyte1_e32 v141, v131
	v_cvt_f32_ubyte0_e32 v140, v131
	v_cvt_f32_ubyte3_e32 v143, v131
	v_cvt_f32_ubyte2_e32 v142, v131
	v_cvt_f32_ubyte1_e32 v131, v144
	v_cvt_f32_ubyte0_e32 v130, v144
	v_pk_mul_f32 v[132:133], v[14:15], v[132:133]
	v_cvt_f32_ubyte3_e32 v145, v144
	v_cvt_f32_ubyte2_e32 v144, v144
	v_cvt_f32_ubyte1_e32 v147, v148
	v_cvt_f32_ubyte0_e32 v146, v148
	v_cvt_f32_ubyte3_e32 v149, v148
	v_cvt_f32_ubyte2_e32 v148, v148
	v_pk_mul_f32 v[138:139], v[16:17], v[138:139]
	v_pk_mul_f32 v[142:143], v[12:13], v[142:143]
	v_pk_mul_f32 v[140:141], v[10:11], v[140:141]
	v_pk_mul_f32 v[150:151], v[6:7], v[130:131]
	v_cvt_pk_bf16_f32 v130, v132, v133
	v_cvt_pk_bf16_f32 v131, v138, v139
	v_cvt_pk_bf16_f32 v132, v140, v141
	v_cvt_pk_bf16_f32 v133, v142, v143
	v_pk_mul_f32 v[144:145], v[8:9], v[144:145]
	v_pk_mul_f32 v[148:149], v[4:5], v[148:149]
	v_pk_mul_f32 v[146:147], v[2:3], v[146:147]
	global_store_dwordx4 v[134:135], v[130:133], off offset:256
	s_nop 1
	v_cvt_pk_bf16_f32 v130, v150, v151
	v_cvt_pk_bf16_f32 v131, v144, v145
	v_cvt_pk_bf16_f32 v132, v146, v147
	v_cvt_pk_bf16_f32 v133, v148, v149
	global_store_dwordx4 v[136:137], v[130:133], off offset:256
	s_andn2_b64 vcc, exec, s[2:3]
	s_mov_b64 s[2:3], -1
	s_cbranch_vccnz .LBB0_526

	.amdhsa_kernel _Z14fwd_megakernel4Args
		.amdhsa_group_segment_fixed_size 0
		.amdhsa_private_segment_fixed_size 0
		.amdhsa_kernarg_size 456
		.amdhsa_user_sgpr_count 2
		.amdhsa_user_sgpr_dispatch_ptr 0
		.amdhsa_user_sgpr_queue_ptr 0
		.amdhsa_user_sgpr_kernarg_segment_ptr 1
		.amdhsa_user_sgpr_dispatch_id 0
		.amdhsa_user_sgpr_kernarg_preload_length 0
		.amdhsa_user_sgpr_kernarg_preload_offset 0
		.amdhsa_user_sgpr_private_segment_size 0
		.amdhsa_uses_dynamic_stack 0
		.amdhsa_enable_private_segment 0
		.amdhsa_system_sgpr_workgroup_id_x 1
		.amdhsa_system_sgpr_workgroup_id_y 0
		.amdhsa_system_sgpr_workgroup_id_z 0
		.amdhsa_system_sgpr_workgroup_info 0
		.amdhsa_system_vgpr_workitem_id 0
		.amdhsa_next_free_vgpr 256
		.amdhsa_next_free_sgpr 102
		.amdhsa_accum_offset 256
		.amdhsa_reserve_vcc 1
		.amdhsa_float_round_mode_32 0
		.amdhsa_float_round_mode_16_64 0
		.amdhsa_float_denorm_mode_32 3
		.amdhsa_float_denorm_mode_16_64 3
		.amdhsa_dx10_clamp 1
		.amdhsa_ieee_mode 1
		.amdhsa_fp16_overflow 0
		.amdhsa_tg_split 0
		.amdhsa_exception_fp_ieee_invalid_op 0
		.amdhsa_exception_fp_denorm_src 0
		.amdhsa_exception_fp_ieee_div_zero 0
		.amdhsa_exception_fp_ieee_overflow 0
		.amdhsa_exception_fp_ieee_underflow 0
		.amdhsa_exception_fp_ieee_inexact 0
		.amdhsa_exception_int_div_zero 0
	.end_amdhsa_kernel

amdhsa.kernels:
  - .agpr_count:     0
    .args:
      - .offset:         0
        .size:           200
        .value_kind:     by_value
      - .offset:         200
        .size:           4
        .value_kind:     hidden_block_count_x
      - .offset:         204
        .size:           4
        .value_kind:     hidden_block_count_y
      - .offset:         208
        .size:           4
        .value_kind:     hidden_block_count_z
      - .offset:         212
        .size:           2
        .value_kind:     hidden_group_size_x
      - .offset:         214
        .size:           2
        .value_kind:     hidden_group_size_y
      - .offset:         216
        .size:           2
        .value_kind:     hidden_group_size_z
      - .offset:         218
        .size:           2
        .value_kind:     hidden_remainder_x
      - .offset:         220
        .size:           2
        .value_kind:     hidden_remainder_y
      - .offset:         222
        .size:           2
        .value_kind:     hidden_remainder_z
      - .offset:         240
        .size:           8
        .value_kind:     hidden_global_offset_x
      - .offset:         248
        .size:           8
        .value_kind:     hidden_global_offset_y
      - .offset:         256
        .size:           8
        .value_kind:     hidden_global_offset_z
      - .offset:         264
        .size:           2
        .value_kind:     hidden_grid_dims
      - .offset:         320
        .size:           4
        .value_kind:     hidden_dynamic_lds_size
    .group_segment_fixed_size: 0
    .kernarg_segment_align: 8
    .kernarg_segment_size: 456
    .language:       OpenCL C
    .language_version:
      - 2
      - 0
    .max_flat_workgroup_size: 512
    .name:           _Z14fwd_megakernel4Args
    .private_segment_fixed_size: 0
    .sgpr_count:     108
    .sgpr_spill_count: 64
    .symbol:         _Z14fwd_megakernel4Args.kd
    .uniform_work_group_size: 1
    .uses_dynamic_stack: false
    .vgpr_count:     256
    .vgpr_spill_count: 0
    .wavefront_size: 64
